# kernel prologue row phase: the 16 norm-weight chunks loaded once before the row loop instead of one per store behind vmcnt(0)
# speedup vs baseline: 1.0029x; 1.0007x over previous
.LBB0_29:
	s_or_b64 exec, exec, s[14:15]
	s_mov_b64 s[14:15], s[22:23]
	s_mov_b64 s[16:17], s[22:23]
	v_mov_b32_e32 v2, v236
	s_movk_i32 s1, 0x4000
	v_ashrrev_i32_e32 v3, 4, v2
	v_and_b32_e32 v3, -4, v3
	v_lshrrev_b32_e32 v1, 4, v2
	v_lshl_add_u32 v3, s2, 5, v3
	v_and_or_b32 v66, v1, 3, v3
	v_cmp_gt_i32_e32 vcc, s1, v66
	v_mbcnt_lo_u32_b32 v1, -1, 0
	s_and_saveexec_b64 s[4:5], vcc
	s_cbranch_execz .LBB0_32
	v_lshlrev_b32_e32 v2, 2, v2
	v_and_b32_e32 v68, 60, v2
	v_mbcnt_hi_u32_b32 v2, -1, v1
	v_and_b32_e32 v5, 64, v2
	v_xor_b32_e32 v4, 8, v2
	v_add_u32_e32 v5, 64, v5
	v_cmp_lt_i32_e32 vcc, v4, v5
	s_load_dwordx2 s[18:19], s[16:17], 0x78
	s_load_dwordx2 s[6:7], s[14:15], 0x0
	s_load_dwordx2 s[20:21], s[14:15], 0x68
	v_cndmask_b32_e32 v4, v2, v4, vcc
	v_lshlrev_b32_e32 v69, 2, v4
	v_xor_b32_e32 v4, 4, v2
	v_cmp_lt_i32_e32 vcc, v4, v5
	s_waitcnt lgkmcnt(0)
	s_add_u32 s14, s18, 0x3700000
	v_mov_b32_e32 v3, 0
	v_cndmask_b32_e32 v4, v2, v4, vcc
	v_lshlrev_b32_e32 v75, 2, v4
	v_xor_b32_e32 v4, 2, v2
	v_cmp_lt_i32_e32 vcc, v4, v5
	s_addc_u32 s15, s19, 0
	s_lshl_b32 s1, s56, 5
	v_cndmask_b32_e32 v4, v2, v4, vcc
	v_lshlrev_b32_e32 v76, 2, v4
	v_xor_b32_e32 v4, 1, v2
	v_cmp_lt_i32_e32 vcc, v4, v5
	s_mov_b64 s[16:17], 0
	v_mov_b32_e32 v78, 0x358637bd
	v_cndmask_b32_e32 v2, v2, v4, vcc
	v_lshlrev_b32_e32 v77, 2, v2
	v_lshlrev_b32_e32 v2, 2, v68
	v_lshl_add_u64 v[70:71], s[20:21], 0, v[2:3]
	s_movk_i32 s3, 0x3fff
	global_load_dwordx4 v[110:113], v[70:71], off
	global_load_dwordx4 v[114:117], v[70:71], off offset:256
	global_load_dwordx4 v[118:121], v[70:71], off offset:512
	global_load_dwordx4 v[122:125], v[70:71], off offset:768
	global_load_dwordx4 v[126:129], v[70:71], off offset:1024
	global_load_dwordx4 v[130:133], v[70:71], off offset:1280
	global_load_dwordx4 v[134:137], v[70:71], off offset:1536
	global_load_dwordx4 v[138:141], v[70:71], off offset:1792
	global_load_dwordx4 v[142:145], v[70:71], off offset:2048
	global_load_dwordx4 v[146:149], v[70:71], off offset:2304
	global_load_dwordx4 v[150:153], v[70:71], off offset:2560
	global_load_dwordx4 v[154:157], v[70:71], off offset:2816
	global_load_dwordx4 v[158:161], v[70:71], off offset:3072
	global_load_dwordx4 v[162:165], v[70:71], off offset:3328
	global_load_dwordx4 v[166:169], v[70:71], off offset:3584
	global_load_dwordx4 v[170:173], v[70:71], off offset:3840
.LBB0_31:
	v_ashrrev_i32_e32 v67, 31, v66
	v_lshlrev_b64 v[72:73], 10, v[66:67]
	v_or_b32_e32 v72, v72, v68
	v_lshl_add_u64 v[84:85], v[72:73], 2, s[6:7]
	global_load_dwordx4 v[34:37], v[84:85], off
	global_load_dwordx4 v[30:33], v[84:85], off offset:256
	global_load_dwordx4 v[26:29], v[84:85], off offset:512
	global_load_dwordx4 v[14:17], v[84:85], off offset:3072
	global_load_dwordx4 v[10:13], v[84:85], off offset:3328
	global_load_dwordx4 v[6:9], v[84:85], off offset:3584
	global_load_dwordx4 v[2:5], v[84:85], off offset:3840
	global_load_dwordx4 v[22:25], v[84:85], off offset:768
	global_load_dwordx4 v[18:21], v[84:85], off offset:1024
	global_load_dwordx4 v[62:65], v[84:85], off offset:1280
	global_load_dwordx4 v[58:61], v[84:85], off offset:1536
	global_load_dwordx4 v[54:57], v[84:85], off offset:1792
	global_load_dwordx4 v[50:53], v[84:85], off offset:2048
	global_load_dwordx4 v[46:49], v[84:85], off offset:2304
	global_load_dwordx4 v[42:45], v[84:85], off offset:2560
	global_load_dwordx4 v[38:41], v[84:85], off offset:2816
	v_lshl_add_u64 v[72:73], v[72:73], 1, s[14:15]
	v_add_u32_e32 v66, s1, v66
	v_cmp_lt_i32_e32 vcc, s3, v66
	s_or_b64 s[16:17], vcc, s[16:17]
	s_waitcnt vmcnt(15)
	v_mul_f32_e32 v67, v35, v35
	s_waitcnt vmcnt(14)
	v_mul_f32_e32 v74, v31, v31
	s_waitcnt vmcnt(13)
	v_mul_f32_e32 v79, v27, v27
	v_fmac_f32_e32 v67, v34, v34
	v_fmac_f32_e32 v74, v30, v30
	v_fmac_f32_e32 v79, v26, v26
	v_fmac_f32_e32 v67, v36, v36
	s_waitcnt vmcnt(8)
	v_mul_f32_e32 v97, v23, v23
	v_fmac_f32_e32 v74, v32, v32
	s_waitcnt vmcnt(7)
	v_mul_f32_e32 v98, v19, v19
	v_fmac_f32_e32 v97, v22, v22
	v_fmac_f32_e32 v79, v28, v28
	v_fmac_f32_e32 v67, v37, v37
	v_fmac_f32_e32 v74, v33, v33
	s_waitcnt vmcnt(6)
	v_mul_f32_e32 v99, v63, v63
	v_fmac_f32_e32 v98, v18, v18
	v_fmac_f32_e32 v97, v24, v24
	v_fmac_f32_e32 v79, v29, v29
	v_add_f32_e32 v67, v67, v74
	s_waitcnt vmcnt(5)
	v_mul_f32_e32 v100, v59, v59
	v_fmac_f32_e32 v99, v62, v62
	v_fmac_f32_e32 v98, v20, v20
	v_fmac_f32_e32 v97, v25, v25
	v_add_f32_e32 v67, v67, v79
	s_waitcnt vmcnt(4)
	v_mul_f32_e32 v101, v55, v55
	v_fmac_f32_e32 v100, v58, v58
	v_fmac_f32_e32 v99, v64, v64
	v_fmac_f32_e32 v98, v21, v21
	v_add_f32_e32 v67, v67, v97
	s_waitcnt vmcnt(3)
	v_mul_f32_e32 v102, v51, v51
	v_fmac_f32_e32 v101, v54, v54
	v_fmac_f32_e32 v100, v60, v60
	v_fmac_f32_e32 v99, v65, v65
	v_add_f32_e32 v67, v67, v98
	s_waitcnt vmcnt(2)
	v_mul_f32_e32 v103, v47, v47
	v_fmac_f32_e32 v102, v50, v50
	v_fmac_f32_e32 v101, v56, v56
	v_fmac_f32_e32 v100, v61, v61
	v_add_f32_e32 v67, v67, v99
	s_waitcnt vmcnt(1)
	v_mul_f32_e32 v104, v43, v43
	v_fmac_f32_e32 v103, v46, v46
	v_fmac_f32_e32 v102, v52, v52
	v_fmac_f32_e32 v101, v57, v57
	v_add_f32_e32 v67, v67, v100
	v_mov_b32_e32 v86, v15
	v_mov_b32_e32 v87, v11
	s_waitcnt vmcnt(0)
	v_mul_f32_e32 v105, v39, v39
	v_fmac_f32_e32 v104, v42, v42
	v_fmac_f32_e32 v103, v48, v48
	v_fmac_f32_e32 v102, v53, v53
	v_add_f32_e32 v67, v67, v101
	v_mov_b32_e32 v84, v14
	v_mov_b32_e32 v85, v10
	v_pk_mul_f32 v[86:87], v[86:87], v[86:87]
	v_fmac_f32_e32 v105, v38, v38
	v_fmac_f32_e32 v104, v44, v44
	v_fmac_f32_e32 v103, v49, v49
	v_add_f32_e32 v67, v67, v102
	v_mov_b32_e32 v92, v16
	v_mov_b32_e32 v93, v12
	v_pk_fma_f32 v[84:85], v[84:85], v[84:85], v[86:87]
	v_fmac_f32_e32 v105, v40, v40
	v_fmac_f32_e32 v104, v45, v45
	v_add_f32_e32 v67, v67, v103
	v_mov_b32_e32 v90, v7
	v_mov_b32_e32 v91, v3
	v_mov_b32_e32 v94, v17
	v_mov_b32_e32 v95, v13
	v_pk_fma_f32 v[84:85], v[92:93], v[92:93], v[84:85]
	v_fmac_f32_e32 v105, v41, v41
	v_add_f32_e32 v67, v67, v104
	v_mov_b32_e32 v88, v6
	v_mov_b32_e32 v89, v2
	v_pk_mul_f32 v[90:91], v[90:91], v[90:91]
	v_pk_fma_f32 v[84:85], v[94:95], v[94:95], v[84:85]
	v_add_f32_e32 v67, v67, v105
	v_mov_b32_e32 v96, v8
	v_pk_fma_f32 v[86:87], v[88:89], v[88:89], v[90:91]
	v_add_f32_e32 v67, v67, v84
	v_mov_b32_e32 v97, v4
	v_add_f32_e32 v67, v67, v85
	v_pk_fma_f32 v[84:85], v[96:97], v[96:97], v[86:87]
	v_mov_b32_e32 v86, v9
	v_mov_b32_e32 v87, v5
	v_pk_fma_f32 v[84:85], v[86:87], v[86:87], v[84:85]
	s_nop 0
	v_add_f32_e32 v67, v67, v84
	v_add_f32_e32 v67, v67, v85
	ds_bpermute_b32 v74, v69, v67
	s_waitcnt lgkmcnt(0)
	v_add_f32_e32 v67, v67, v74
	ds_bpermute_b32 v74, v75, v67
	s_waitcnt lgkmcnt(0)
	v_add_f32_e32 v67, v67, v74
	ds_bpermute_b32 v74, v76, v67
	s_waitcnt lgkmcnt(0)
	v_add_f32_e32 v67, v67, v74
	ds_bpermute_b32 v74, v77, v67
	s_waitcnt lgkmcnt(0)
	v_add_f32_e32 v67, v67, v74
	v_fmamk_f32 v67, v67, 0x3a800000, v78
	v_rsq_f32_e32 v74, v67
	s_nop 0
	v_pk_mul_f32 v[34:35], v[34:35], v[74:75] op_sel_hi:[1,0]
	v_pk_mul_f32 v[36:37], v[36:37], v[74:75] op_sel_hi:[1,0]
	v_pk_mul_f32 v[34:35], v[110:111], v[34:35]
	v_pk_mul_f32 v[36:37], v[112:113], v[36:37]
	v_cvt_pk_bf16_f32 v34, v34, v35
	v_cvt_pk_bf16_f32 v35, v36, v37
	global_store_dwordx2 v[72:73], v[34:35], off
	v_pk_mul_f32 v[30:31], v[30:31], v[74:75] op_sel_hi:[1,0]
	v_pk_mul_f32 v[32:33], v[32:33], v[74:75] op_sel_hi:[1,0]
	v_pk_mul_f32 v[30:31], v[114:115], v[30:31]
	v_pk_mul_f32 v[32:33], v[116:117], v[32:33]
	v_cvt_pk_bf16_f32 v30, v30, v31
	v_cvt_pk_bf16_f32 v31, v32, v33
	global_store_dwordx2 v[72:73], v[30:31], off offset:128
	v_pk_mul_f32 v[26:27], v[26:27], v[74:75] op_sel_hi:[1,0]
	v_pk_mul_f32 v[28:29], v[28:29], v[74:75] op_sel_hi:[1,0]
	v_pk_mul_f32 v[26:27], v[118:119], v[26:27]
	v_pk_mul_f32 v[28:29], v[120:121], v[28:29]
	v_cvt_pk_bf16_f32 v26, v26, v27
	v_cvt_pk_bf16_f32 v27, v28, v29
	global_store_dwordx2 v[72:73], v[26:27], off offset:256
	v_pk_mul_f32 v[22:23], v[22:23], v[74:75] op_sel_hi:[1,0]
	v_pk_mul_f32 v[24:25], v[24:25], v[74:75] op_sel_hi:[1,0]
	v_pk_mul_f32 v[22:23], v[122:123], v[22:23]
	v_pk_mul_f32 v[24:25], v[124:125], v[24:25]
	v_cvt_pk_bf16_f32 v22, v22, v23
	v_cvt_pk_bf16_f32 v23, v24, v25
	global_store_dwordx2 v[72:73], v[22:23], off offset:384
	v_pk_mul_f32 v[18:19], v[18:19], v[74:75] op_sel_hi:[1,0]
	v_pk_mul_f32 v[20:21], v[20:21], v[74:75] op_sel_hi:[1,0]
	v_pk_mul_f32 v[18:19], v[126:127], v[18:19]
	v_pk_mul_f32 v[20:21], v[128:129], v[20:21]
	v_cvt_pk_bf16_f32 v18, v18, v19
	v_cvt_pk_bf16_f32 v19, v20, v21
	global_store_dwordx2 v[72:73], v[18:19], off offset:512
	v_pk_mul_f32 v[62:63], v[62:63], v[74:75] op_sel_hi:[1,0]
	v_pk_mul_f32 v[64:65], v[64:65], v[74:75] op_sel_hi:[1,0]
	v_pk_mul_f32 v[62:63], v[130:131], v[62:63]
	v_pk_mul_f32 v[64:65], v[132:133], v[64:65]
	v_cvt_pk_bf16_f32 v62, v62, v63
	v_cvt_pk_bf16_f32 v63, v64, v65
	global_store_dwordx2 v[72:73], v[62:63], off offset:640
	v_pk_mul_f32 v[58:59], v[58:59], v[74:75] op_sel_hi:[1,0]
	v_pk_mul_f32 v[60:61], v[60:61], v[74:75] op_sel_hi:[1,0]
	v_pk_mul_f32 v[58:59], v[134:135], v[58:59]
	v_pk_mul_f32 v[60:61], v[136:137], v[60:61]
	v_cvt_pk_bf16_f32 v58, v58, v59
	v_cvt_pk_bf16_f32 v59, v60, v61
	global_store_dwordx2 v[72:73], v[58:59], off offset:768
	v_pk_mul_f32 v[54:55], v[54:55], v[74:75] op_sel_hi:[1,0]
	v_pk_mul_f32 v[56:57], v[56:57], v[74:75] op_sel_hi:[1,0]
	v_pk_mul_f32 v[54:55], v[138:139], v[54:55]
	v_pk_mul_f32 v[56:57], v[140:141], v[56:57]
	v_cvt_pk_bf16_f32 v54, v54, v55
	v_cvt_pk_bf16_f32 v55, v56, v57
	global_store_dwordx2 v[72:73], v[54:55], off offset:896
	v_pk_mul_f32 v[50:51], v[50:51], v[74:75] op_sel_hi:[1,0]
	v_pk_mul_f32 v[52:53], v[52:53], v[74:75] op_sel_hi:[1,0]
	v_pk_mul_f32 v[50:51], v[142:143], v[50:51]
	v_pk_mul_f32 v[52:53], v[144:145], v[52:53]
	v_cvt_pk_bf16_f32 v50, v50, v51
	v_cvt_pk_bf16_f32 v51, v52, v53
	global_store_dwordx2 v[72:73], v[50:51], off offset:1024
	v_pk_mul_f32 v[46:47], v[46:47], v[74:75] op_sel_hi:[1,0]
	v_pk_mul_f32 v[48:49], v[48:49], v[74:75] op_sel_hi:[1,0]
	v_pk_mul_f32 v[46:47], v[146:147], v[46:47]
	v_pk_mul_f32 v[48:49], v[148:149], v[48:49]
	v_cvt_pk_bf16_f32 v46, v46, v47
	v_cvt_pk_bf16_f32 v47, v48, v49
	global_store_dwordx2 v[72:73], v[46:47], off offset:1152
	v_pk_mul_f32 v[42:43], v[42:43], v[74:75] op_sel_hi:[1,0]
	v_pk_mul_f32 v[44:45], v[44:45], v[74:75] op_sel_hi:[1,0]
	v_pk_mul_f32 v[42:43], v[150:151], v[42:43]
	v_pk_mul_f32 v[44:45], v[152:153], v[44:45]
	v_cvt_pk_bf16_f32 v42, v42, v43
	v_cvt_pk_bf16_f32 v43, v44, v45
	global_store_dwordx2 v[72:73], v[42:43], off offset:1280
	v_pk_mul_f32 v[38:39], v[38:39], v[74:75] op_sel_hi:[1,0]
	v_pk_mul_f32 v[40:41], v[40:41], v[74:75] op_sel_hi:[1,0]
	v_pk_mul_f32 v[38:39], v[154:155], v[38:39]
	v_pk_mul_f32 v[40:41], v[156:157], v[40:41]
	v_cvt_pk_bf16_f32 v38, v38, v39
	v_cvt_pk_bf16_f32 v39, v40, v41
	global_store_dwordx2 v[72:73], v[38:39], off offset:1408
	v_pk_mul_f32 v[14:15], v[14:15], v[74:75] op_sel_hi:[1,0]
	v_pk_mul_f32 v[16:17], v[16:17], v[74:75] op_sel_hi:[1,0]
	v_pk_mul_f32 v[14:15], v[158:159], v[14:15]
	v_pk_mul_f32 v[16:17], v[160:161], v[16:17]
	v_cvt_pk_bf16_f32 v14, v14, v15
	v_cvt_pk_bf16_f32 v15, v16, v17
	global_store_dwordx2 v[72:73], v[14:15], off offset:1536
	v_pk_mul_f32 v[10:11], v[10:11], v[74:75] op_sel_hi:[1,0]
	v_pk_mul_f32 v[12:13], v[12:13], v[74:75] op_sel_hi:[1,0]
	v_pk_mul_f32 v[10:11], v[162:163], v[10:11]
	v_pk_mul_f32 v[12:13], v[164:165], v[12:13]
	v_cvt_pk_bf16_f32 v10, v10, v11
	v_cvt_pk_bf16_f32 v11, v12, v13
	global_store_dwordx2 v[72:73], v[10:11], off offset:1664
	v_pk_mul_f32 v[6:7], v[6:7], v[74:75] op_sel_hi:[1,0]
	v_pk_mul_f32 v[8:9], v[8:9], v[74:75] op_sel_hi:[1,0]
	v_pk_mul_f32 v[6:7], v[166:167], v[6:7]
	v_pk_mul_f32 v[8:9], v[168:169], v[8:9]
	v_cvt_pk_bf16_f32 v6, v6, v7
	v_cvt_pk_bf16_f32 v7, v8, v9
	global_store_dwordx2 v[72:73], v[6:7], off offset:1792
	v_pk_mul_f32 v[2:3], v[2:3], v[74:75] op_sel_hi:[1,0]
	v_pk_mul_f32 v[4:5], v[4:5], v[74:75] op_sel_hi:[1,0]
	v_pk_mul_f32 v[2:3], v[170:171], v[2:3]
	v_pk_mul_f32 v[4:5], v[172:173], v[4:5]
	v_cvt_pk_bf16_f32 v2, v2, v3
	v_cvt_pk_bf16_f32 v3, v4, v5
	global_store_dwordx2 v[72:73], v[2:3], off offset:1920
	s_andn2_b64 exec, exec, s[16:17]
	s_cbranch_execnz .LBB0_31
